# GU: next-unit rss loads issued at epilogue start (older than stores); exact-intent vmcnt(19) in first K-iteration phases 1-2 of non-first units
# speedup vs baseline: 1.0270x; 1.0046x over previous
; DI float rss_sum(const float* rss, int row) {
;     const f32x4* p = (const f32x4*)(rss + (size_t)row * 16); const f32x4 a = p[0], b = p[1], c = p[2], d = p[3];
;     return (((a.x + a.y) + (a.z + a.w)) + ((b.x + b.y) + (b.z + b.w))) + (((c.x + c.y) + (c.z + c.w)) + ((d.x + d.y) + (d.z + d.w))); }
; template <class Epi>
; DI void gemm_phase(LAS unsigned char* lds, const int tid, const Gemm g, const StaticOrder& S, const Epi& E) {
;     ...
;     for (;;) {
;         const bool has_next = S.next(ui + 1, nxt);
;         const char* nA = has_next ? (const char*)g.A + (size_t)nxt.pm * tstepA : cA; const char* nB = has_next ? (const char*)g.Bt + (size_t)nxt.pn * tstepB : cB;
.LBB0_666:
	s_cmp_lg_u32 s46, 1
	s_cselect_b32 s100, 1, 0
	s_cbranch_scc1 .Lgu_noR0
	v_readlane_b32 s26, v253, 49
	s_lshl_b32 s27, s49, 14
	s_nop 1
	s_add_u32 s26, s26, s27
	v_readlane_b32 s27, v253, 50
	s_nop 1
	s_addc_u32 s27, s27, 0
	s_nop 4
	global_load_dwordx4 v[228:231], v252, s[26:27]
	global_load_dwordx2 v[232:233], v252, s[26:27] offset:16
	global_load_dwordx2 v[238:239], v252, s[26:27] offset:24

; #define PG8_STAGE(bufoff, gbase, voff) do { _Pragma("unroll") for (int _i = 0; _i < 2; ++_i) \
;         __builtin_amdgcn_global_load_lds((const unsigned*)((const char*)(gbase) + (voff)[_i]), (LAS unsigned*)(lds + (bufoff) + ldsw + _i * 8192), 16, 0, 0); } while (0)
; #define PG8_LDA(dst, b, h) do { _Pragma("unroll") for (int m = 0; m < 4; ++m) _Pragma("unroll") for (int k = 0; k < 2; ++k) dst[m][k] = *(const LAS bf16x8*)(lds + PG8_SA(b, h) + aoff + m * 2048 + k * 1024); } while (0)
; #define PG8_LDB(dst, b, h) do { _Pragma("unroll") for (int n = 0; n < 2; ++n) _Pragma("unroll") for (int k = 0; k < 2; ++k) dst[n][k] = *(const LAS bf16x8*)(lds + PG8_SB(b, h) + boff + n * 2048 + k * 1024); } while (0)
; #define PG8_MMA(ai, bj, At, Bt) do { __builtin_amdgcn_s_setprio(1); _Pragma("unroll") for (int m = 0; m < 4; ++m) _Pragma("unroll") for (int n = 0; n < 2; ++n) _Pragma("unroll") for (int k = 0; k < 2; ++k) \
;         acc[ai][bj][m][n] = __builtin_amdgcn_mfma_f32_16x16x32_bf16(Bt[n][k], At[m][k], acc[ai][bj][m][n], 0, 0, 0); __builtin_amdgcn_s_setprio(0); } while (0)
; #define PG8_WAIT_V(n) asm volatile("s_waitcnt vmcnt(" #n ")" ::: "memory")
; #define PG8_WAIT_L(n) asm volatile("s_waitcnt lgkmcnt(" #n ")" ::: "memory")
; #define PG8_BAR __builtin_amdgcn_s_barrier()
; #define PG8_SCHED __builtin_amdgcn_sched_barrier(0)
; template <class Epi>
; DI void gemm_phase(LAS unsigned char* lds, const int tid, const Gemm g, const StaticOrder& S, const Epi& E) {
;     ...
;             PG8_LDB(B0, 0, 0); PG8_LDB(B1, 0, 1); PG8_SCHED; PG8_LDA(At, 0, 0); PG8_STAGE(PG8_SA(1, 1), a1 + hstepA, voffA);
;             PG8_WAIT_V(8); PG8_WAIT_L(0); PG8_BAR; PG8_MMA(0, 0, At, B0); PG8_MMA(0, 1, At, B1); PG8_BAR; PG8_SCHED;
;             PG8_LDA(At, 0, 1); PG8_STAGE(PG8_SB(0, 0), b2, voffB); PG8_STAGE(PG8_SB(0, 1), b2 + hstepB, voffB); PG8_STAGE(PG8_SA(0, 0), a2, voffA);
;             PG8_WAIT_V(8); PG8_WAIT_L(0); PG8_BAR; PG8_MMA(1, 0, At, B0); PG8_MMA(1, 1, At, B1); PG8_BAR; PG8_SCHED;
.Lgu_rs_skip:
	s_add_u32 s36, s6, 0xfffc0080
	s_addc_u32 s37, s7, -1
	s_add_i32 s59, 0, 0x10000
	s_cmp_eq_u32 s58, 12
	s_cselect_b32 s41, s13, s37
	s_cselect_b32 s40, s52, s36
	v_add_u32_e32 v140, s59, v147
	s_cselect_b32 s37, s11, s57
	s_cselect_b32 s36, s53, s56
	s_add_i32 s62, 0, 0x14000
	ds_read_b128 v[156:159], v140
	ds_read_b128 v[160:163], v140 offset:1024
	ds_read_b128 v[164:167], v140 offset:2048
	ds_read_b128 v[168:171], v140 offset:3072
	v_add_u32_e32 v140, s62, v147
	ds_read_b128 v[172:175], v140
	ds_read_b128 v[176:179], v140 offset:1024
	ds_read_b128 v[180:183], v140 offset:2048
	ds_read_b128 v[184:187], v140 offset:3072
	v_lshl_add_u64 v[140:141], s[6:7], 0, v[136:137]
	s_add_i32 m0, s30, 0xc000
	ds_read_b128 v[188:191], v155
	ds_read_b128 v[192:195], v155 offset:1024
	ds_read_b128 v[196:199], v155 offset:2048
	ds_read_b128 v[208:211], v155 offset:3072
	ds_read_b128 v[212:215], v155 offset:4096
	ds_read_b128 v[216:219], v155 offset:5120
	ds_read_b128 v[220:223], v155 offset:6144
	ds_read_b128 v[224:227], v155 offset:7168
	global_load_lds_dwordx4 v[140:141], off
	v_lshl_add_u64 v[140:141], s[6:7], 0, v[138:139]
	s_add_i32 m0, s30, 0xe000
	s_nop 0
	global_load_lds_dwordx4 v[140:141], off
	s_cmp_eq_u32 s100, 0
	s_cbranch_scc1 .Lgu_ws1
	s_waitcnt vmcnt(19)
	s_branch .Lgu_wd1
.Lgu_ws1:
	s_waitcnt vmcnt(8)
.Lgu_wd1:
	s_waitcnt lgkmcnt(0)
	s_barrier
	s_setprio 1
	s_waitcnt lgkmcnt(0)
	v_mfma_f32_16x16x32_bf16 v[126:129], v[156:159], v[188:191], v[126:129]
	v_mfma_f32_16x16x32_bf16 v[118:121], v[164:167], v[188:191], v[118:121]
	v_mfma_f32_16x16x32_bf16 v[110:113], v[156:159], v[196:199], v[110:113]
	v_mfma_f32_16x16x32_bf16 v[102:105], v[164:167], v[196:199], v[102:105]
	v_mfma_f32_16x16x32_bf16 v[94:97], v[156:159], v[212:215], v[94:97]
	v_mfma_f32_16x16x32_bf16 v[86:89], v[164:167], v[212:215], v[86:89]
	v_mfma_f32_16x16x32_bf16 v[78:81], v[156:159], v[220:223], v[78:81]
	v_mfma_f32_16x16x32_bf16 v[70:73], v[164:167], v[220:223], v[70:73]
	v_mfma_f32_16x16x32_bf16 v[126:129], v[160:163], v[192:195], v[126:129]
	v_mfma_f32_16x16x32_bf16 v[118:121], v[168:171], v[192:195], v[118:121]
	v_mfma_f32_16x16x32_bf16 v[110:113], v[160:163], v[208:211], v[110:113]
	v_mfma_f32_16x16x32_bf16 v[102:105], v[168:171], v[208:211], v[102:105]
	v_mfma_f32_16x16x32_bf16 v[94:97], v[160:163], v[216:219], v[94:97]
	v_mfma_f32_16x16x32_bf16 v[86:89], v[168:171], v[216:219], v[86:89]
	v_mfma_f32_16x16x32_bf16 v[78:81], v[160:163], v[224:227], v[78:81]
	v_mfma_f32_16x16x32_bf16 v[70:73], v[168:171], v[224:227], v[70:73]
	s_setprio 0
	s_setprio 1
	v_mfma_f32_16x16x32_bf16 v[122:125], v[172:175], v[188:191], v[122:125]
	v_mfma_f32_16x16x32_bf16 v[114:117], v[180:183], v[188:191], v[114:117]
	v_mfma_f32_16x16x32_bf16 v[106:109], v[172:175], v[196:199], v[106:109]
	v_mfma_f32_16x16x32_bf16 v[98:101], v[180:183], v[196:199], v[98:101]
	v_mfma_f32_16x16x32_bf16 v[90:93], v[172:175], v[212:215], v[90:93]
	v_mfma_f32_16x16x32_bf16 v[82:85], v[180:183], v[212:215], v[82:85]
	v_mfma_f32_16x16x32_bf16 v[74:77], v[172:175], v[220:223], v[74:77]
	v_mfma_f32_16x16x32_bf16 v[66:69], v[180:183], v[220:223], v[66:69]
	v_mfma_f32_16x16x32_bf16 v[122:125], v[176:179], v[192:195], v[122:125]
	v_mfma_f32_16x16x32_bf16 v[114:117], v[184:187], v[192:195], v[114:117]
	v_mfma_f32_16x16x32_bf16 v[106:109], v[176:179], v[208:211], v[106:109]
	v_mfma_f32_16x16x32_bf16 v[98:101], v[184:187], v[208:211], v[98:101]
	v_mfma_f32_16x16x32_bf16 v[90:93], v[176:179], v[216:219], v[90:93]
	v_mfma_f32_16x16x32_bf16 v[82:85], v[184:187], v[216:219], v[82:85]
	v_mfma_f32_16x16x32_bf16 v[74:77], v[176:179], v[224:227], v[74:77]
	v_mfma_f32_16x16x32_bf16 v[66:69], v[184:187], v[224:227], v[66:69]
	s_setprio 0
	s_barrier
	s_add_i32 s59, s59, s25
	v_lshl_add_u64 v[140:141], s[36:37], 0, v[0:1]
	s_mov_b32 m0, s59
	ds_read_b128 v[188:191], v155 offset:16384
	ds_read_b128 v[192:195], v155 offset:17408
	ds_read_b128 v[196:199], v155 offset:18432
	ds_read_b128 v[208:211], v155 offset:19456
	ds_read_b128 v[212:215], v155 offset:20480
	ds_read_b128 v[216:219], v155 offset:21504
	ds_read_b128 v[220:223], v155 offset:22528
	ds_read_b128 v[224:227], v155 offset:23552
	global_load_lds_dwordx4 v[140:141], off
	s_add_i32 m0, s59, 0x2000
	s_add_u32 s60, s36, 0x40000
	v_lshl_add_u64 v[148:149], s[36:37], 0, v[130:131]
	s_addc_u32 s61, s37, 0
	s_add_i32 s59, s62, s25
	global_load_lds_dwordx4 v[148:149], off
	v_lshl_add_u64 v[200:201], s[60:61], 0, v[0:1]
	s_mov_b32 m0, s59
	v_lshl_add_u64 v[202:203], s[40:41], 0, v[132:133]
	global_load_lds_dwordx4 v[200:201], off
	v_lshl_add_u64 v[200:201], s[60:61], 0, v[130:131]
	s_add_i32 m0, s59, 0x2000
	s_nop 0
	global_load_lds_dwordx4 v[200:201], off
	v_lshl_add_u64 v[200:201], s[40:41], 0, v[134:135]
	s_mov_b32 m0, s30
	s_nop 0
	global_load_lds_dwordx4 v[200:201], off
	s_mov_b32 m0, s31
	s_nop 0
	global_load_lds_dwordx4 v[202:203], off
	s_cmp_eq_u32 s100, 0
	s_cbranch_scc1 .Lgu_ws2
	s_waitcnt vmcnt(19)
	s_mov_b32 s100, 0
	s_branch .Lgu_wd2

; #define PG8_STAGE(bufoff, gbase, voff) do { _Pragma("unroll") for (int _i = 0; _i < 2; ++_i) \
;         __builtin_amdgcn_global_load_lds((const unsigned*)((const char*)(gbase) + (voff)[_i]), (LAS unsigned*)(lds + (bufoff) + ldsw + _i * 8192), 16, 0, 0); } while (0)
; #define PG8_LDA(dst, b, h) do { _Pragma("unroll") for (int m = 0; m < 4; ++m) _Pragma("unroll") for (int k = 0; k < 2; ++k) dst[m][k] = *(const LAS bf16x8*)(lds + PG8_SA(b, h) + aoff + m * 2048 + k * 1024); } while (0)
; #define PG8_LDB(dst, b, h) do { _Pragma("unroll") for (int n = 0; n < 2; ++n) _Pragma("unroll") for (int k = 0; k < 2; ++k) dst[n][k] = *(const LAS bf16x8*)(lds + PG8_SB(b, h) + boff + n * 2048 + k * 1024); } while (0)
; #define PG8_MMA(ai, bj, At, Bt) do { __builtin_amdgcn_s_setprio(1); _Pragma("unroll") for (int m = 0; m < 4; ++m) _Pragma("unroll") for (int n = 0; n < 2; ++n) _Pragma("unroll") for (int k = 0; k < 2; ++k) \
;         acc[ai][bj][m][n] = __builtin_amdgcn_mfma_f32_16x16x32_bf16(Bt[n][k], At[m][k], acc[ai][bj][m][n], 0, 0, 0); __builtin_amdgcn_s_setprio(0); } while (0)
; #define PG8_WAIT_V(n) asm volatile("s_waitcnt vmcnt(" #n ")" ::: "memory")
; #define PG8_WAIT_L(n) asm volatile("s_waitcnt lgkmcnt(" #n ")" ::: "memory")
; #define PG8_BAR __builtin_amdgcn_s_barrier()
; #define PG8_SCHED __builtin_amdgcn_sched_barrier(0)
; template <class Epi>
; DI void gemm_phase(LAS unsigned char* lds, const int tid, const Gemm g, const StaticOrder& S, const Epi& E) {
;     ...
;             PG8_WAIT_V(8); PG8_WAIT_L(0); PG8_BAR; PG8_MMA(1, 0, At, B0); PG8_MMA(1, 1, At, B1); PG8_BAR; PG8_SCHED;
;             PG8_LDB(B0, 1, 0); PG8_LDB(B1, 1, 1); PG8_SCHED; PG8_LDA(At, 1, 0); PG8_STAGE(PG8_SA(0, 1), a2 + hstepA, voffA);
;             PG8_WAIT_V(8); PG8_WAIT_L(0); PG8_BAR; PG8_MMA(0, 0, At, B0); PG8_MMA(0, 1, At, B1); PG8_BAR; PG8_SCHED;
.Lgu_wd2:
	s_waitcnt lgkmcnt(0)
	s_barrier
	s_setprio 1
	s_waitcnt lgkmcnt(0)
	v_mfma_f32_16x16x32_bf16 v[62:65], v[156:159], v[188:191], v[62:65]
	v_mfma_f32_16x16x32_bf16 v[54:57], v[164:167], v[188:191], v[54:57]
	v_mfma_f32_16x16x32_bf16 v[46:49], v[156:159], v[196:199], v[46:49]
	v_mfma_f32_16x16x32_bf16 v[38:41], v[164:167], v[196:199], v[38:41]
	v_mfma_f32_16x16x32_bf16 v[30:33], v[156:159], v[212:215], v[30:33]
	v_mfma_f32_16x16x32_bf16 v[22:25], v[164:167], v[212:215], v[22:25]
	v_mfma_f32_16x16x32_bf16 v[14:17], v[156:159], v[220:223], v[14:17]
	v_mfma_f32_16x16x32_bf16 v[6:9], v[164:167], v[220:223], v[6:9]
	v_mfma_f32_16x16x32_bf16 v[62:65], v[160:163], v[192:195], v[62:65]
	v_mfma_f32_16x16x32_bf16 v[54:57], v[168:171], v[192:195], v[54:57]
	v_mfma_f32_16x16x32_bf16 v[46:49], v[160:163], v[208:211], v[46:49]
	v_mfma_f32_16x16x32_bf16 v[38:41], v[168:171], v[208:211], v[38:41]
	v_mfma_f32_16x16x32_bf16 v[30:33], v[160:163], v[216:219], v[30:33]
	v_mfma_f32_16x16x32_bf16 v[22:25], v[168:171], v[216:219], v[22:25]
	v_mfma_f32_16x16x32_bf16 v[14:17], v[160:163], v[224:227], v[14:17]
	v_mfma_f32_16x16x32_bf16 v[6:9], v[168:171], v[224:227], v[6:9]
	s_setprio 0
	s_setprio 1
	v_mfma_f32_16x16x32_bf16 v[58:61], v[172:175], v[188:191], v[58:61]
	v_mfma_f32_16x16x32_bf16 v[50:53], v[180:183], v[188:191], v[50:53]
	v_mfma_f32_16x16x32_bf16 v[42:45], v[172:175], v[196:199], v[42:45]
	v_mfma_f32_16x16x32_bf16 v[34:37], v[180:183], v[196:199], v[34:37]
	v_mfma_f32_16x16x32_bf16 v[26:29], v[172:175], v[212:215], v[26:29]
	v_mfma_f32_16x16x32_bf16 v[18:21], v[180:183], v[212:215], v[18:21]
	v_mfma_f32_16x16x32_bf16 v[10:13], v[172:175], v[220:223], v[10:13]
	v_mfma_f32_16x16x32_bf16 v[2:5], v[180:183], v[220:223], v[2:5]
	v_mfma_f32_16x16x32_bf16 v[58:61], v[176:179], v[192:195], v[58:61]
	v_mfma_f32_16x16x32_bf16 v[50:53], v[184:187], v[192:195], v[50:53]
	v_mfma_f32_16x16x32_bf16 v[42:45], v[176:179], v[208:211], v[42:45]
	v_mfma_f32_16x16x32_bf16 v[34:37], v[184:187], v[208:211], v[34:37]
	v_mfma_f32_16x16x32_bf16 v[26:29], v[176:179], v[216:219], v[26:29]
	v_mfma_f32_16x16x32_bf16 v[18:21], v[184:187], v[216:219], v[18:21]
	v_mfma_f32_16x16x32_bf16 v[10:13], v[176:179], v[224:227], v[10:13]
	v_mfma_f32_16x16x32_bf16 v[2:5], v[184:187], v[224:227], v[2:5]
	s_setprio 0
	s_barrier
	s_add_i32 s59, 0, 0x18000
	v_add_u32_e32 v142, s59, v147
	s_add_i32 s60, 0, 0x1c000
	ds_read_b128 v[156:159], v142
	ds_read_b128 v[160:163], v142 offset:1024
	ds_read_b128 v[164:167], v142 offset:2048
	ds_read_b128 v[168:171], v142 offset:3072
	v_add_u32_e32 v142, s60, v147
	ds_read_b128 v[172:175], v142
	ds_read_b128 v[176:179], v142 offset:1024
	ds_read_b128 v[180:183], v142 offset:2048
	ds_read_b128 v[184:187], v142 offset:3072
	s_add_u32 s40, s40, 0x40000
	s_addc_u32 s41, s41, 0
	s_mov_b32 m0, s38
	v_lshl_add_u64 v[204:205], s[40:41], 0, v[134:135]
	ds_read_b128 v[188:191], v155 offset:32768
	ds_read_b128 v[192:195], v155 offset:33792
	ds_read_b128 v[196:199], v155 offset:34816
	ds_read_b128 v[208:211], v155 offset:35840
	ds_read_b128 v[212:215], v155 offset:36864
	ds_read_b128 v[216:219], v155 offset:37888
	ds_read_b128 v[220:223], v155 offset:38912
	ds_read_b128 v[224:227], v155 offset:39936
	global_load_lds_dwordx4 v[204:205], off
	v_lshl_add_u64 v[204:205], s[40:41], 0, v[132:133]
	s_mov_b32 m0, s39
	s_nop 0
	global_load_lds_dwordx4 v[204:205], off
	s_waitcnt vmcnt(8)
	s_waitcnt lgkmcnt(0)
	s_barrier
	s_setprio 1
	s_waitcnt lgkmcnt(0)
	v_mfma_f32_16x16x32_bf16 v[126:129], v[156:159], v[188:191], v[126:129]
	v_mfma_f32_16x16x32_bf16 v[118:121], v[164:167], v[188:191], v[118:121]
	v_mfma_f32_16x16x32_bf16 v[110:113], v[156:159], v[196:199], v[110:113]
	v_mfma_f32_16x16x32_bf16 v[102:105], v[164:167], v[196:199], v[102:105]
	v_mfma_f32_16x16x32_bf16 v[94:97], v[156:159], v[212:215], v[94:97]
	v_mfma_f32_16x16x32_bf16 v[86:89], v[164:167], v[212:215], v[86:89]
	v_mfma_f32_16x16x32_bf16 v[78:81], v[156:159], v[220:223], v[78:81]
	v_mfma_f32_16x16x32_bf16 v[70:73], v[164:167], v[220:223], v[70:73]
	v_mfma_f32_16x16x32_bf16 v[126:129], v[160:163], v[192:195], v[126:129]
	v_mfma_f32_16x16x32_bf16 v[118:121], v[168:171], v[192:195], v[118:121]
	v_mfma_f32_16x16x32_bf16 v[110:113], v[160:163], v[208:211], v[110:113]
	v_mfma_f32_16x16x32_bf16 v[102:105], v[168:171], v[208:211], v[102:105]
	v_mfma_f32_16x16x32_bf16 v[94:97], v[160:163], v[216:219], v[94:97]
	v_mfma_f32_16x16x32_bf16 v[86:89], v[168:171], v[216:219], v[86:89]
	v_mfma_f32_16x16x32_bf16 v[78:81], v[160:163], v[224:227], v[78:81]
	v_mfma_f32_16x16x32_bf16 v[70:73], v[168:171], v[224:227], v[70:73]
	s_setprio 0
	s_setprio 1
	v_mfma_f32_16x16x32_bf16 v[122:125], v[172:175], v[188:191], v[122:125]
	v_mfma_f32_16x16x32_bf16 v[114:117], v[180:183], v[188:191], v[114:117]
	v_mfma_f32_16x16x32_bf16 v[106:109], v[172:175], v[196:199], v[106:109]
	v_mfma_f32_16x16x32_bf16 v[98:101], v[180:183], v[196:199], v[98:101]
	v_mfma_f32_16x16x32_bf16 v[90:93], v[172:175], v[212:215], v[90:93]
	v_mfma_f32_16x16x32_bf16 v[82:85], v[180:183], v[212:215], v[82:85]
	v_mfma_f32_16x16x32_bf16 v[74:77], v[172:175], v[220:223], v[74:77]
	v_mfma_f32_16x16x32_bf16 v[66:69], v[180:183], v[220:223], v[66:69]
	v_mfma_f32_16x16x32_bf16 v[122:125], v[176:179], v[192:195], v[122:125]
	v_mfma_f32_16x16x32_bf16 v[114:117], v[184:187], v[192:195], v[114:117]
	v_mfma_f32_16x16x32_bf16 v[106:109], v[176:179], v[208:211], v[106:109]
	v_mfma_f32_16x16x32_bf16 v[98:101], v[184:187], v[208:211], v[98:101]
	v_mfma_f32_16x16x32_bf16 v[90:93], v[176:179], v[216:219], v[90:93]
	v_mfma_f32_16x16x32_bf16 v[82:85], v[184:187], v[216:219], v[82:85]
	v_mfma_f32_16x16x32_bf16 v[74:77], v[176:179], v[224:227], v[74:77]
	v_mfma_f32_16x16x32_bf16 v[66:69], v[184:187], v[224:227], v[66:69]
	s_setprio 0
	s_barrier
; #define PG8_STAGE(bufoff, gbase, voff) do { _Pragma("unroll") for (int _i = 0; _i < 2; ++_i) \
;         __builtin_amdgcn_global_load_lds((const unsigned*)((const char*)(gbase) + (voff)[_i]), (LAS unsigned*)(lds + (bufoff) + ldsw + _i * 8192), 16, 0, 0); } while (0)
; #define PG8_LDA(dst, b, h) do { _Pragma("unroll") for (int m = 0; m < 4; ++m) _Pragma("unroll") for (int k = 0; k < 2; ++k) dst[m][k] = *(const LAS bf16x8*)(lds + PG8_SA(b, h) + aoff + m * 2048 + k * 1024); } while (0)
; #define PG8_MMA(ai, bj, At, Bt) do { __builtin_amdgcn_s_setprio(1); _Pragma("unroll") for (int m = 0; m < 4; ++m) _Pragma("unroll") for (int n = 0; n < 2; ++n) _Pragma("unroll") for (int k = 0; k < 2; ++k) \
;         acc[ai][bj][m][n] = __builtin_amdgcn_mfma_f32_16x16x32_bf16(Bt[n][k], At[m][k], acc[ai][bj][m][n], 0, 0, 0); __builtin_amdgcn_s_setprio(0); } while (0)
; #define PG8_WAIT_V(n) asm volatile("s_waitcnt vmcnt(" #n ")" ::: "memory")
; #define PG8_WAIT_L(n) asm volatile("s_waitcnt lgkmcnt(" #n ")" ::: "memory")
; #define PG8_BAR __builtin_amdgcn_s_barrier()
; #define PG8_SCHED __builtin_amdgcn_sched_barrier(0)
; DI float rss_sum(const float* rss, int row) {
;     const f32x4* p = (const f32x4*)(rss + (size_t)row * 16); const f32x4 a = p[0], b = p[1], c = p[2], d = p[3];
;     return (((a.x + a.y) + (a.z + a.w)) + ((b.x + b.y) + (b.z + b.w))) + (((c.x + c.y) + (c.z + c.w)) + ((d.x + d.y) + (d.z + d.w))); }
; template <class Epi>
; DI void gemm_phase(LAS unsigned char* lds, const int tid, const Gemm g, const StaticOrder& S, const Epi& E) {
;     ...
;             PG8_LDA(At, 1, 1); PG8_STAGE(PG8_SB(1, 0), b3, voffB); PG8_STAGE(PG8_SB(1, 1), b3 + hstepB, voffB); PG8_STAGE(PG8_SA(1, 0), a3, voffA);
;             PG8_WAIT_V(8); PG8_WAIT_L(0); PG8_BAR; PG8_MMA(1, 0, At, B0); PG8_MMA(1, 1, At, B1); PG8_BAR; PG8_SCHED;
;         }
;         if (wr == 0) PG8_BAR;
;         E(acc, cur, wr, wc, fr, fq);
	s_add_i32 s40, s59, s25
	v_lshl_add_u64 v[140:141], v[140:141], 0, s[54:55]
	s_mov_b32 m0, s40
	ds_read_b128 v[188:191], v155 offset:49152
	ds_read_b128 v[192:195], v155 offset:50176
	ds_read_b128 v[196:199], v155 offset:51200
	ds_read_b128 v[208:211], v155 offset:52224
	ds_read_b128 v[212:215], v155 offset:53248
	ds_read_b128 v[216:219], v155 offset:54272
	ds_read_b128 v[220:223], v155 offset:55296
	ds_read_b128 v[224:227], v155 offset:56320
	global_load_lds_dwordx4 v[140:141], off
	s_add_i32 m0, s40, 0x2000
	s_add_u32 s36, s36, 0x40080
	v_lshl_add_u64 v[140:141], v[148:149], 0, s[54:55]
	s_addc_u32 s37, s37, 0
	s_add_i32 s40, s60, s25
	global_load_lds_dwordx4 v[140:141], off
	v_lshl_add_u64 v[140:141], s[36:37], 0, v[0:1]
	s_mov_b32 m0, s40
	s_nop 0
	global_load_lds_dwordx4 v[140:141], off
	v_lshl_add_u64 v[140:141], s[36:37], 0, v[130:131]
	s_add_i32 m0, s40, 0x2000
	s_nop 0
	global_load_lds_dwordx4 v[140:141], off
	v_lshl_add_u64 v[140:141], v[200:201], 0, s[54:55]
	s_mov_b32 m0, s42
	s_nop 0
	global_load_lds_dwordx4 v[140:141], off
	v_lshl_add_u64 v[140:141], v[202:203], 0, s[54:55]
	s_mov_b32 m0, s43
	s_nop 0
	global_load_lds_dwordx4 v[140:141], off
	s_waitcnt vmcnt(8)
	s_waitcnt lgkmcnt(0)
	s_barrier
	s_setprio 1
	s_waitcnt lgkmcnt(0)
	v_mfma_f32_16x16x32_bf16 v[62:65], v[156:159], v[188:191], v[62:65]
	v_mfma_f32_16x16x32_bf16 v[54:57], v[164:167], v[188:191], v[54:57]
	v_mfma_f32_16x16x32_bf16 v[46:49], v[156:159], v[196:199], v[46:49]
	v_mfma_f32_16x16x32_bf16 v[38:41], v[164:167], v[196:199], v[38:41]
	v_mfma_f32_16x16x32_bf16 v[30:33], v[156:159], v[212:215], v[30:33]
	v_mfma_f32_16x16x32_bf16 v[22:25], v[164:167], v[212:215], v[22:25]
	v_mfma_f32_16x16x32_bf16 v[14:17], v[156:159], v[220:223], v[14:17]
	v_mfma_f32_16x16x32_bf16 v[6:9], v[164:167], v[220:223], v[6:9]
	v_mfma_f32_16x16x32_bf16 v[62:65], v[160:163], v[192:195], v[62:65]
	v_mfma_f32_16x16x32_bf16 v[54:57], v[168:171], v[192:195], v[54:57]
	v_mfma_f32_16x16x32_bf16 v[46:49], v[160:163], v[208:211], v[46:49]
	v_mfma_f32_16x16x32_bf16 v[38:41], v[168:171], v[208:211], v[38:41]
	v_mfma_f32_16x16x32_bf16 v[30:33], v[160:163], v[216:219], v[30:33]
	v_mfma_f32_16x16x32_bf16 v[22:25], v[168:171], v[216:219], v[22:25]
	v_mfma_f32_16x16x32_bf16 v[14:17], v[160:163], v[224:227], v[14:17]
	v_mfma_f32_16x16x32_bf16 v[6:9], v[168:171], v[224:227], v[6:9]
	s_setprio 0
	s_setprio 1
	v_mfma_f32_16x16x32_bf16 v[58:61], v[172:175], v[188:191], v[58:61]
	v_mfma_f32_16x16x32_bf16 v[50:53], v[180:183], v[188:191], v[50:53]
	v_mfma_f32_16x16x32_bf16 v[42:45], v[172:175], v[196:199], v[42:45]
	v_mfma_f32_16x16x32_bf16 v[34:37], v[180:183], v[196:199], v[34:37]
	v_mfma_f32_16x16x32_bf16 v[26:29], v[172:175], v[212:215], v[26:29]
	v_mfma_f32_16x16x32_bf16 v[18:21], v[180:183], v[212:215], v[18:21]
	v_mfma_f32_16x16x32_bf16 v[10:13], v[172:175], v[220:223], v[10:13]
	v_mfma_f32_16x16x32_bf16 v[2:5], v[180:183], v[220:223], v[2:5]
	v_mfma_f32_16x16x32_bf16 v[58:61], v[176:179], v[192:195], v[58:61]
	v_mfma_f32_16x16x32_bf16 v[50:53], v[184:187], v[192:195], v[50:53]
	v_mfma_f32_16x16x32_bf16 v[42:45], v[176:179], v[208:211], v[42:45]
	v_mfma_f32_16x16x32_bf16 v[34:37], v[184:187], v[208:211], v[34:37]
	v_mfma_f32_16x16x32_bf16 v[26:29], v[176:179], v[216:219], v[26:29]
	v_mfma_f32_16x16x32_bf16 v[18:21], v[184:187], v[216:219], v[18:21]
	v_mfma_f32_16x16x32_bf16 v[10:13], v[176:179], v[224:227], v[10:13]
	v_mfma_f32_16x16x32_bf16 v[2:5], v[184:187], v[224:227], v[2:5]
	s_setprio 0
	s_barrier
	s_add_i32 s58, s58, 2
	s_add_u32 s6, s6, 0x100
	s_addc_u32 s7, s7, 0
	s_add_u32 s56, s56, 0x100
	s_addc_u32 s57, s57, 0
	s_cmp_gt_u32 s58, 13
	s_cbranch_scc0 .LBB0_667
	s_and_b64 vcc, exec, s[8:9]
	s_cbranch_vccz .LBB0_670
	s_barrier
.LBB0_670:
	s_andn2_b64 vcc, exec, s[4:5]
	s_cbranch_vccnz .Lgu_noR
	v_readlane_b32 s36, v253, 49
	s_and_b32 s37, s12, 0x7f
	s_lshl_b32 s37, s37, 14
	s_nop 0
	s_add_u32 s36, s36, s37
	v_readlane_b32 s37, v253, 50
	s_nop 1
	s_addc_u32 s37, s37, 0
	s_nop 4
	global_load_dwordx4 v[228:231], v252, s[36:37]
	global_load_dwordx2 v[232:233], v252, s[36:37] offset:16
	global_load_dwordx2 v[238:239], v252, s[36:37] offset:24
